# RetIn projection epilogue: fast path for column tiles without rotary (plain rstd scale + pack)
# speedup vs baseline: 1.0023x; 1.0023x over previous
; #define LAS __attribute__((address_space(3)))
; __device__ __forceinline__ unsigned pack2(float lo, float hi) { const f32x2_t v = {lo, hi}; const bf16x2_t b = __builtin_convertvector(v, bf16x2_t); return __builtin_bit_cast(unsigned, b); }
; template <class Epi>
; __device__ __forceinline__ void gemm_phase(LAS unsigned char* lds, const Gemm g, const Epi& E) {
;     ...
;         E(acc, cur, wr, wc, fr, fq, rstab + (cur.pm == tag1 ? 256 : cur.pm == tag2 ? 512 : cur.pm == tag3 ? 768 : 0));
;     __device__ __forceinline__ void operator()(AccRef acc, const Unit& u, int wr, int wc, int fr, int fq, const LAS float* rsl) const {
;         const int row0 = u.pm * 256 + wr * 64 + fr, col0 = u.pn * 256 + wc * 32 + 8 * fq, f = 16 * wc + 4 * fq;
; #pragma unroll
;         for (int ai = 0; ai < 2; ++ai)
; #pragma unroll
;             for (int m = 0; m < 4; ++m) { const int r = row0 + ai * 128 + m * 16; bf16_t* rowp = O + (size_t)r * ldc + col0; const float rs = rsl[ai * 128 + wr * 64 + m * 16 + fr];
;                 f32x4 c4 = (f32x4){1.f, 1.f, 1.f, 1.f}, s4 = (f32x4){0.f, 0.f, 0.f, 0.f};
;                 if (u.pn < 8) { const int pos = (rowbase + r) & 8191; c4 = *(const f32x4*)(cs + pos * 64 + f); s4 = *(const f32x4*)(sn + pos * 64 + f);
;                     if (u.pn >= 4) { c4 *= 0.08838834764831845f; s4 *= 0.08838834764831845f; } }
; #pragma unroll
;                 for (int bj = 0; bj < 2; ++bj) { const f32x4 t1 = rs * acc[ai][bj][m][0], t2 = rs * acc[ai][bj][m][1]; const f32x4 v0 = t1 * c4 - t2 * s4, v1 = t1 * s4 + t2 * c4;
;                     uint4 w; w.x = pack2(v0[0], v0[1]); w.y = pack2(v0[2], v0[3]); w.z = pack2(v1[0], v1[1]); w.w = pack2(v1[2], v1[3]);
;                     *(uint4*)(rowp + bj * 128) = w; } }
.LBB0_995:
	s_cmp_gt_i32 s44, 7
	s_cbranch_scc0 .Lretin_rot
	s_cmp_eq_u32 s42, s16
	s_cselect_b32 s20, 0x300, 0
	s_cmp_lg_u32 s42, s13
	s_cselect_b32 s20, s20, 0x200
	s_cmp_lg_u32 s42, s12
	s_cselect_b32 s20, s20, 0x100
	v_lshl_add_u32 v165, s20, 2, v162
	ds_read_b32 v152, v165
	ds_read_b32 v154, v165 offset:64
	ds_read_b32 v156, v165 offset:128
	ds_read_b32 v158, v165 offset:192
	ds_read_b32 v168, v165 offset:512
	ds_read_b32 v170, v165 offset:576
	ds_read_b32 v146, v165 offset:640
	ds_read_b32 v148, v165 offset:704
	v_lshl_add_u32 v164, s42, 8, v151
	v_lshl_or_b32 v144, s44, 8, v161
	s_movk_i32 s24, 0x3000
	v_lshlrev_b32_e32 v144, 1, v144
	v_mad_u32_u24 v166, v164, s24, v144
	v_mov_b32_e32 v249, v229
	v_mov_b32_e32 v248, v190
	v_mov_b32_e32 v250, v230
	s_waitcnt lgkmcnt(0)
	v_pk_mul_f32 v[124:125], v[124:125], v[152:153] op_sel_hi:[1,0]
	v_pk_mul_f32 v[126:127], v[126:127], v[152:153] op_sel_hi:[1,0]
	v_pk_mul_f32 v[120:121], v[120:121], v[152:153] op_sel_hi:[1,0]
	v_pk_mul_f32 v[122:123], v[122:123], v[152:153] op_sel_hi:[1,0]
	v_cvt_pk_bf16_f32 v123, v122, v123
	v_cvt_pk_bf16_f32 v122, v120, v121
	v_cvt_pk_bf16_f32 v120, v124, v125
	v_cvt_pk_bf16_f32 v121, v126, v127
	global_store_dwordx4 v166, v[120:123], s[14:15]
	v_pk_mul_f32 v[116:117], v[116:117], v[152:153] op_sel_hi:[1,0]
	v_pk_mul_f32 v[118:119], v[118:119], v[152:153] op_sel_hi:[1,0]
	v_pk_mul_f32 v[112:113], v[112:113], v[152:153] op_sel_hi:[1,0]
	v_pk_mul_f32 v[114:115], v[114:115], v[152:153] op_sel_hi:[1,0]
	v_cvt_pk_bf16_f32 v115, v114, v115
	v_cvt_pk_bf16_f32 v114, v112, v113
	v_cvt_pk_bf16_f32 v112, v116, v117
	v_cvt_pk_bf16_f32 v113, v118, v119
	global_store_dwordx4 v166, v[112:115], s[14:15] offset:256
	v_add_u32_e32 v167, 0x30000, v166
	v_pk_mul_f32 v[108:109], v[108:109], v[154:155] op_sel_hi:[1,0]
	v_pk_mul_f32 v[110:111], v[110:111], v[154:155] op_sel_hi:[1,0]
	v_pk_mul_f32 v[104:105], v[104:105], v[154:155] op_sel_hi:[1,0]
	v_pk_mul_f32 v[106:107], v[106:107], v[154:155] op_sel_hi:[1,0]
	v_cvt_pk_bf16_f32 v107, v106, v107
	v_cvt_pk_bf16_f32 v106, v104, v105
	v_cvt_pk_bf16_f32 v104, v108, v109
	v_cvt_pk_bf16_f32 v105, v110, v111
	global_store_dwordx4 v167, v[104:107], s[14:15]
	v_pk_mul_f32 v[100:101], v[100:101], v[154:155] op_sel_hi:[1,0]
	v_pk_mul_f32 v[102:103], v[102:103], v[154:155] op_sel_hi:[1,0]
	v_pk_mul_f32 v[96:97], v[96:97], v[154:155] op_sel_hi:[1,0]
	v_pk_mul_f32 v[98:99], v[98:99], v[154:155] op_sel_hi:[1,0]
	v_cvt_pk_bf16_f32 v99, v98, v99
	v_cvt_pk_bf16_f32 v98, v96, v97
	v_cvt_pk_bf16_f32 v96, v100, v101
	v_cvt_pk_bf16_f32 v97, v102, v103
	global_store_dwordx4 v167, v[96:99], s[14:15] offset:256
	v_add_u32_e32 v167, 0x60000, v166
	v_pk_mul_f32 v[92:93], v[92:93], v[156:157] op_sel_hi:[1,0]
	v_pk_mul_f32 v[94:95], v[94:95], v[156:157] op_sel_hi:[1,0]
	v_pk_mul_f32 v[88:89], v[88:89], v[156:157] op_sel_hi:[1,0]
	v_pk_mul_f32 v[90:91], v[90:91], v[156:157] op_sel_hi:[1,0]
	v_cvt_pk_bf16_f32 v91, v90, v91
	v_cvt_pk_bf16_f32 v90, v88, v89
	v_cvt_pk_bf16_f32 v88, v92, v93
	v_cvt_pk_bf16_f32 v89, v94, v95
	global_store_dwordx4 v167, v[88:91], s[14:15]
	v_pk_mul_f32 v[84:85], v[84:85], v[156:157] op_sel_hi:[1,0]
	v_pk_mul_f32 v[86:87], v[86:87], v[156:157] op_sel_hi:[1,0]
	v_pk_mul_f32 v[80:81], v[80:81], v[156:157] op_sel_hi:[1,0]
	v_pk_mul_f32 v[82:83], v[82:83], v[156:157] op_sel_hi:[1,0]
	v_cvt_pk_bf16_f32 v83, v82, v83
	v_cvt_pk_bf16_f32 v82, v80, v81
	v_cvt_pk_bf16_f32 v80, v84, v85
	v_cvt_pk_bf16_f32 v81, v86, v87
	global_store_dwordx4 v167, v[80:83], s[14:15] offset:256
	v_add_u32_e32 v167, 0x90000, v166
	v_pk_mul_f32 v[76:77], v[76:77], v[158:159] op_sel_hi:[1,0]
	v_pk_mul_f32 v[78:79], v[78:79], v[158:159] op_sel_hi:[1,0]
	v_pk_mul_f32 v[72:73], v[72:73], v[158:159] op_sel_hi:[1,0]
	v_pk_mul_f32 v[74:75], v[74:75], v[158:159] op_sel_hi:[1,0]
	v_cvt_pk_bf16_f32 v75, v74, v75
	v_cvt_pk_bf16_f32 v74, v72, v73
	v_cvt_pk_bf16_f32 v72, v76, v77
	v_cvt_pk_bf16_f32 v73, v78, v79
	global_store_dwordx4 v167, v[72:75], s[14:15]
; __device__ __forceinline__ unsigned pack2(float lo, float hi) { const f32x2_t v = {lo, hi}; const bf16x2_t b = __builtin_convertvector(v, bf16x2_t); return __builtin_bit_cast(unsigned, b); }
; template <class Epi>
; __device__ __forceinline__ void gemm_phase(LAS unsigned char* lds, const Gemm g, const Epi& E) {
;     ...
;         if (!has_next) break;
;     __device__ __forceinline__ void operator()(AccRef acc, const Unit& u, int wr, int wc, int fr, int fq, const LAS float* rsl) const {
;     ...
;         for (int ai = 0; ai < 2; ++ai)
; #pragma unroll
;             for (int m = 0; m < 4; ++m) { const int r = row0 + ai * 128 + m * 16; bf16_t* rowp = O + (size_t)r * ldc + col0; const float rs = rsl[ai * 128 + wr * 64 + m * 16 + fr];
;                 f32x4 c4 = (f32x4){1.f, 1.f, 1.f, 1.f}, s4 = (f32x4){0.f, 0.f, 0.f, 0.f};
;                 if (u.pn < 8) { const int pos = (rowbase + r) & 8191; c4 = *(const f32x4*)(cs + pos * 64 + f); s4 = *(const f32x4*)(sn + pos * 64 + f);
;                     if (u.pn >= 4) { c4 *= 0.08838834764831845f; s4 *= 0.08838834764831845f; } }
; #pragma unroll
;                 for (int bj = 0; bj < 2; ++bj) { const f32x4 t1 = rs * acc[ai][bj][m][0], t2 = rs * acc[ai][bj][m][1]; const f32x4 v0 = t1 * c4 - t2 * s4, v1 = t1 * s4 + t2 * c4;
;                     uint4 w; w.x = pack2(v0[0], v0[1]); w.y = pack2(v0[2], v0[3]); w.z = pack2(v1[0], v1[1]); w.w = pack2(v1[2], v1[3]);
;                     *(uint4*)(rowp + bj * 128) = w; } }
	v_pk_mul_f32 v[68:69], v[68:69], v[158:159] op_sel_hi:[1,0]
	v_pk_mul_f32 v[70:71], v[70:71], v[158:159] op_sel_hi:[1,0]
	v_pk_mul_f32 v[64:65], v[64:65], v[158:159] op_sel_hi:[1,0]
	v_pk_mul_f32 v[66:67], v[66:67], v[158:159] op_sel_hi:[1,0]
	v_cvt_pk_bf16_f32 v67, v66, v67
	v_cvt_pk_bf16_f32 v66, v64, v65
	v_cvt_pk_bf16_f32 v64, v68, v69
	v_cvt_pk_bf16_f32 v65, v70, v71
	global_store_dwordx4 v167, v[64:67], s[14:15] offset:256
	v_add_u32_e32 v167, 0x180000, v166
	v_pk_mul_f32 v[60:61], v[60:61], v[168:169] op_sel_hi:[1,0]
	v_pk_mul_f32 v[62:63], v[62:63], v[168:169] op_sel_hi:[1,0]
	v_pk_mul_f32 v[56:57], v[56:57], v[168:169] op_sel_hi:[1,0]
	v_pk_mul_f32 v[58:59], v[58:59], v[168:169] op_sel_hi:[1,0]
	v_cvt_pk_bf16_f32 v59, v58, v59
	v_cvt_pk_bf16_f32 v58, v56, v57
	v_cvt_pk_bf16_f32 v56, v60, v61
	v_cvt_pk_bf16_f32 v57, v62, v63
	global_store_dwordx4 v167, v[56:59], s[14:15]
	v_pk_mul_f32 v[52:53], v[52:53], v[168:169] op_sel_hi:[1,0]
	v_pk_mul_f32 v[54:55], v[54:55], v[168:169] op_sel_hi:[1,0]
	v_pk_mul_f32 v[48:49], v[48:49], v[168:169] op_sel_hi:[1,0]
	v_pk_mul_f32 v[50:51], v[50:51], v[168:169] op_sel_hi:[1,0]
	v_cvt_pk_bf16_f32 v51, v50, v51
	v_cvt_pk_bf16_f32 v50, v48, v49
	v_cvt_pk_bf16_f32 v48, v52, v53
	v_cvt_pk_bf16_f32 v49, v54, v55
	global_store_dwordx4 v167, v[48:51], s[14:15] offset:256
	v_add_u32_e32 v167, 0x1b0000, v166
	v_pk_mul_f32 v[44:45], v[44:45], v[170:171] op_sel_hi:[1,0]
	v_pk_mul_f32 v[46:47], v[46:47], v[170:171] op_sel_hi:[1,0]
	v_pk_mul_f32 v[40:41], v[40:41], v[170:171] op_sel_hi:[1,0]
	v_pk_mul_f32 v[42:43], v[42:43], v[170:171] op_sel_hi:[1,0]
	v_cvt_pk_bf16_f32 v43, v42, v43
	v_cvt_pk_bf16_f32 v42, v40, v41
	v_cvt_pk_bf16_f32 v40, v44, v45
	v_cvt_pk_bf16_f32 v41, v46, v47
	global_store_dwordx4 v167, v[40:43], s[14:15]
	v_pk_mul_f32 v[36:37], v[36:37], v[170:171] op_sel_hi:[1,0]
	v_pk_mul_f32 v[38:39], v[38:39], v[170:171] op_sel_hi:[1,0]
	v_pk_mul_f32 v[32:33], v[32:33], v[170:171] op_sel_hi:[1,0]
	v_pk_mul_f32 v[34:35], v[34:35], v[170:171] op_sel_hi:[1,0]
	v_cvt_pk_bf16_f32 v35, v34, v35
	v_cvt_pk_bf16_f32 v34, v32, v33
	v_cvt_pk_bf16_f32 v32, v36, v37
	v_cvt_pk_bf16_f32 v33, v38, v39
	global_store_dwordx4 v167, v[32:35], s[14:15] offset:256
	v_add_u32_e32 v167, 0x1e0000, v166
	v_pk_mul_f32 v[28:29], v[28:29], v[146:147] op_sel_hi:[1,0]
	v_pk_mul_f32 v[30:31], v[30:31], v[146:147] op_sel_hi:[1,0]
	v_pk_mul_f32 v[24:25], v[24:25], v[146:147] op_sel_hi:[1,0]
	v_pk_mul_f32 v[26:27], v[26:27], v[146:147] op_sel_hi:[1,0]
	v_cvt_pk_bf16_f32 v27, v26, v27
	v_cvt_pk_bf16_f32 v26, v24, v25
	v_cvt_pk_bf16_f32 v24, v28, v29
	v_cvt_pk_bf16_f32 v25, v30, v31
	global_store_dwordx4 v167, v[24:27], s[14:15]
	v_pk_mul_f32 v[20:21], v[20:21], v[146:147] op_sel_hi:[1,0]
	v_pk_mul_f32 v[22:23], v[22:23], v[146:147] op_sel_hi:[1,0]
	v_pk_mul_f32 v[16:17], v[16:17], v[146:147] op_sel_hi:[1,0]
	v_pk_mul_f32 v[18:19], v[18:19], v[146:147] op_sel_hi:[1,0]
	v_cvt_pk_bf16_f32 v19, v18, v19
	v_cvt_pk_bf16_f32 v18, v16, v17
	v_cvt_pk_bf16_f32 v16, v20, v21
	v_cvt_pk_bf16_f32 v17, v22, v23
	global_store_dwordx4 v167, v[16:19], s[14:15] offset:256
	v_add_u32_e32 v167, 0x210000, v166
	v_pk_mul_f32 v[12:13], v[12:13], v[148:149] op_sel_hi:[1,0]
	v_pk_mul_f32 v[14:15], v[14:15], v[148:149] op_sel_hi:[1,0]
	v_pk_mul_f32 v[8:9], v[8:9], v[148:149] op_sel_hi:[1,0]
	v_pk_mul_f32 v[10:11], v[10:11], v[148:149] op_sel_hi:[1,0]
	v_cvt_pk_bf16_f32 v11, v10, v11
	v_cvt_pk_bf16_f32 v10, v8, v9
	v_cvt_pk_bf16_f32 v8, v12, v13
	v_cvt_pk_bf16_f32 v9, v14, v15
	global_store_dwordx4 v167, v[8:11], s[14:15]
	v_pk_mul_f32 v[4:5], v[4:5], v[148:149] op_sel_hi:[1,0]
	v_pk_mul_f32 v[6:7], v[6:7], v[148:149] op_sel_hi:[1,0]
	v_pk_mul_f32 v[0:1], v[0:1], v[148:149] op_sel_hi:[1,0]
	v_pk_mul_f32 v[2:3], v[2:3], v[148:149] op_sel_hi:[1,0]
	v_cvt_pk_bf16_f32 v3, v2, v3
	v_cvt_pk_bf16_f32 v2, v0, v1
	v_cvt_pk_bf16_f32 v0, v4, v5
	v_cvt_pk_bf16_f32 v1, v6, v7
	global_store_dwordx4 v167, v[0:3], s[14:15] offset:256
	s_andn2_b64 vcc, exec, s[40:41]
	s_mov_b64 s[20:21], -1
	s_branch .Lretin_tail

; #define PG8_BAR __builtin_amdgcn_s_barrier()
; template <class Epi>
; __device__ __forceinline__ void gemm_phase(LAS unsigned char* lds, const Gemm g, const Epi& E) {
;     ...
;         if (!has_next) break;
; #pragma unroll
;         for (int a = 0; a < 2; ++a)
; #pragma unroll
;             for (int b = 0; b < 2; ++b)
; #pragma unroll
;                 for (int m = 0; m < 4; ++m)
; #pragma unroll
;                     for (int n = 0; n < 2; ++n) acc[a][b][m][n] = (f32x4){0.f, 0.f, 0.f, 0.f};
;         cur = nxt; cA = nA; cB = nB; ++ui;
;         if (wr == 1) PG8_BAR;
.Lretin_tail:
	s_cbranch_vccnz .LBB0_988
	s_andn2_b64 vcc, exec, s[36:37]
	s_cbranch_vccnz .LBB0_987
	s_barrier
	s_branch .LBB0_987
